# proj GEMM K-loop: 10 s_nop pads replaced by reordering address calc after m0 write, 6 duplicate lgkmcnt(0) removed
# baseline (speedup 1.0000x reference)
; #define PG8_STAGE(bufoff, gbase, voff) do { _Pragma("unroll") for (int _i = 0; _i < 2; ++_i) \
;         __builtin_amdgcn_global_load_lds((const unsigned*)((const char*)(gbase) + (voff)[_i]), (LAS unsigned*)(lds + (bufoff) + ldsw + _i * 8192), 16, 0, 0); } while (0)
; #define PG8_LDA(dst, b, h) do { _Pragma("unroll") for (int m = 0; m < 4; ++m) _Pragma("unroll") for (int k = 0; k < 2; ++k) dst[m][k] = *(const LAS bf16x8*)(lds + PG8_SA(b, h) + aoff + m * 2048 + k * 1024); } while (0)
; #define PG8_LDB(dst, b, h) do { _Pragma("unroll") for (int n = 0; n < 2; ++n) _Pragma("unroll") for (int k = 0; k < 2; ++k) dst[n][k] = *(const LAS bf16x8*)(lds + PG8_SB(b, h) + boff + n * 2048 + k * 1024); } while (0)
; #define PG8_MMA(ai, bj, At, Bt) do { __builtin_amdgcn_s_setprio(1); _Pragma("unroll") for (int m = 0; m < 4; ++m) _Pragma("unroll") for (int n = 0; n < 2; ++n) _Pragma("unroll") for (int k = 0; k < 2; ++k) \
;         acc[ai][bj][m][n] = __builtin_amdgcn_mfma_f32_16x16x32_bf16(Bt[n][k], At[m][k], acc[ai][bj][m][n], 0, 0, 0); __builtin_amdgcn_s_setprio(0); } while (0)
; #define PG8_WAIT_V(n) asm volatile("s_waitcnt vmcnt(" #n ")" ::: "memory")
; template <class Epi>
; DI void gemm_phase(LAS unsigned char* lds, const Gemm g, const StaticOrder& S, const Epi& E) {
;     ...
;         for (int t = 0; t < nt; t += 2) {
;             const bool last = (t == nt - 2);
;             const char* a1 = cA + (size_t)(t + 1) * kstep;
;             const char* a2 = last ? nA : cA + (size_t)(t + 2) * kstep; const char* b2 = last ? nB : cB + (size_t)(t + 2) * kstep;
;             const char* a3 = a2 + kstep; const char* b3 = b2 + kstep;
;             if constexpr (Epi::HAS_MID) { if (t == Epi::MID_T) E.mid(acc, cur, wr, wc, fr, fq); }
;             PG8_LDB(B0, 0, 0); PG8_SCHED; PG8_LDA(At, 0, 0); PG8_STAGE(PG8_SA(1, 1), a1 + hstepA, voffA);
;             PG8_WAIT_L(8); PG8_BAR; PG8_WAIT_L(0); PG8_MMA(0, 0, At, B0); PG8_BAR; PG8_SCHED;
;             PG8_LDB(B1, 0, 1); PG8_STAGE(PG8_SB(0, 0), b2, voffB);
;             PG8_BAR; PG8_WAIT_L(0); PG8_MMA(0, 1, At, B1); PG8_BAR;
;             PG8_LDA(At, 0, 1); PG8_STAGE(PG8_SA(0, 0), a2, voffA);
;             PG8_BAR; PG8_WAIT_L(0); PG8_MMA(1, 0, At, B0); PG8_BAR; PG8_SCHED;
;             PG8_STAGE(PG8_SB(0, 1), b2 + hstepB, voffB);
;             PG8_WAIT_V(6); PG8_BAR; PG8_MMA(1, 1, At, B1); PG8_BAR;
.LBB0_113:
	ds_read_b128 v[150:153], v147
	ds_read_b128 v[154:157], v147 offset:1024
	ds_read_b128 v[158:161], v147 offset:2048
	ds_read_b128 v[162:165], v147 offset:3072
	s_add_u32 s0, s52, 0xfff80080
	s_addc_u32 s1, s53, -1
	s_cmp_eq_u32 s83, 28
	s_cselect_b32 s57, s47, s1
	s_cselect_b32 s56, s79, s0
	s_cselect_b32 s55, s17, s82
	s_cselect_b32 s54, s80, s81
	v_lshl_add_u64 v[170:171], s[52:53], 0, v[136:137]
	s_add_i32 m0, s9, 0xc000
	ds_read_b128 v[166:169], v148
	ds_read_b128 v[174:177], v148 offset:1024
	ds_read_b128 v[178:181], v148 offset:2048
	ds_read_b128 v[182:185], v148 offset:3072
	ds_read_b128 v[186:189], v148 offset:4096
	ds_read_b128 v[190:193], v148 offset:5120
	ds_read_b128 v[194:197], v148 offset:6144
	ds_read_b128 v[198:201], v148 offset:7168
	global_load_lds_dwordx4 v[170:171], off
	s_add_i32 m0, s9, 0xe000
	v_lshl_add_u64 v[170:171], s[52:53], 0, v[138:139]
	global_load_lds_dwordx4 v[170:171], off
	s_waitcnt lgkmcnt(8)
	s_barrier
	s_waitcnt lgkmcnt(0)
	v_mfma_f32_16x16x32_bf16 v[124:127], v[150:153], v[166:169], v[124:127]
	v_mfma_f32_16x16x32_bf16 v[120:123], v[158:161], v[166:169], v[120:123]
	v_mfma_f32_16x16x32_bf16 v[116:119], v[150:153], v[178:181], v[116:119]
	v_mfma_f32_16x16x32_bf16 v[112:115], v[158:161], v[178:181], v[112:115]
	v_mfma_f32_16x16x32_bf16 v[100:103], v[150:153], v[186:189], v[100:103]
	v_mfma_f32_16x16x32_bf16 v[96:99], v[158:161], v[186:189], v[96:99]
	v_mfma_f32_16x16x32_bf16 v[84:87], v[150:153], v[194:197], v[84:87]
	v_mfma_f32_16x16x32_bf16 v[80:83], v[158:161], v[194:197], v[80:83]
	v_mfma_f32_16x16x32_bf16 v[124:127], v[154:157], v[174:177], v[124:127]
	v_mfma_f32_16x16x32_bf16 v[120:123], v[162:165], v[174:177], v[120:123]
	v_mfma_f32_16x16x32_bf16 v[116:119], v[154:157], v[182:185], v[116:119]
	v_mfma_f32_16x16x32_bf16 v[112:115], v[162:165], v[182:185], v[112:115]
	v_mfma_f32_16x16x32_bf16 v[100:103], v[154:157], v[190:193], v[100:103]
	v_mfma_f32_16x16x32_bf16 v[96:99], v[162:165], v[190:193], v[96:99]
	v_mfma_f32_16x16x32_bf16 v[84:87], v[154:157], v[198:201], v[84:87]
	v_mfma_f32_16x16x32_bf16 v[80:83], v[162:165], v[198:201], v[80:83]
	s_barrier
	s_add_i32 s0, s75, s58
	v_lshl_add_u64 v[170:171], s[54:55], 0, v[132:133]
	s_mov_b32 m0, s0
	ds_read_b128 v[202:205], v149
	ds_read_b128 v[206:209], v149 offset:1024
	ds_read_b128 v[210:213], v149 offset:2048
	ds_read_b128 v[216:219], v149 offset:3072
	global_load_lds_dwordx4 v[170:171], off
	s_add_i32 m0, s0, 0x2000
	v_lshl_add_u64 v[220:221], s[54:55], 0, v[128:129]
	global_load_lds_dwordx4 v[220:221], off
	s_barrier
	s_waitcnt lgkmcnt(0)
	v_mfma_f32_16x16x32_bf16 v[108:111], v[202:205], v[166:169], v[108:111]
	v_mfma_f32_16x16x32_bf16 v[104:107], v[210:213], v[166:169], v[104:107]
	v_mfma_f32_16x16x32_bf16 v[92:95], v[202:205], v[178:181], v[92:95]
	v_mfma_f32_16x16x32_bf16 v[88:91], v[210:213], v[178:181], v[88:91]
	v_mfma_f32_16x16x32_bf16 v[76:79], v[202:205], v[186:189], v[76:79]
	v_mfma_f32_16x16x32_bf16 v[72:75], v[210:213], v[186:189], v[72:75]
	v_mfma_f32_16x16x32_bf16 v[68:71], v[202:205], v[194:197], v[68:71]
	v_mfma_f32_16x16x32_bf16 v[64:67], v[210:213], v[194:197], v[64:67]
	v_mfma_f32_16x16x32_bf16 v[108:111], v[206:209], v[174:177], v[108:111]
	v_mfma_f32_16x16x32_bf16 v[104:107], v[216:219], v[174:177], v[104:107]
	v_mfma_f32_16x16x32_bf16 v[92:95], v[206:209], v[182:185], v[92:95]
	v_mfma_f32_16x16x32_bf16 v[88:91], v[216:219], v[182:185], v[88:91]
	v_mfma_f32_16x16x32_bf16 v[76:79], v[206:209], v[190:193], v[76:79]
	v_mfma_f32_16x16x32_bf16 v[72:75], v[216:219], v[190:193], v[72:75]
	v_mfma_f32_16x16x32_bf16 v[68:71], v[206:209], v[198:201], v[68:71]
	v_mfma_f32_16x16x32_bf16 v[64:67], v[216:219], v[198:201], v[64:67]
	s_mov_b32 m0, s9
	v_lshl_add_u64 v[222:223], s[56:57], 0, v[134:135]
	s_barrier
	ds_read_b128 v[166:169], v148 offset:16384
	ds_read_b128 v[174:177], v148 offset:17408
	ds_read_b128 v[178:181], v148 offset:18432
	ds_read_b128 v[182:185], v148 offset:19456
	ds_read_b128 v[186:189], v148 offset:20480
	ds_read_b128 v[190:193], v148 offset:21504
	ds_read_b128 v[194:197], v148 offset:22528
	ds_read_b128 v[198:201], v148 offset:23552
	global_load_lds_dwordx4 v[222:223], off
	s_mov_b32 m0, s61
	v_lshl_add_u64 v[224:225], s[56:57], 0, v[130:131]
	global_load_lds_dwordx4 v[224:225], off
	s_barrier
	s_waitcnt lgkmcnt(0)
	v_mfma_f32_16x16x32_bf16 v[60:63], v[150:153], v[166:169], v[60:63]
	v_mfma_f32_16x16x32_bf16 v[56:59], v[158:161], v[166:169], v[56:59]
	v_mfma_f32_16x16x32_bf16 v[52:55], v[150:153], v[178:181], v[52:55]
	v_mfma_f32_16x16x32_bf16 v[48:51], v[158:161], v[178:181], v[48:51]
	v_mfma_f32_16x16x32_bf16 v[36:39], v[150:153], v[186:189], v[36:39]
	v_mfma_f32_16x16x32_bf16 v[32:35], v[158:161], v[186:189], v[32:35]
	v_mfma_f32_16x16x32_bf16 v[20:23], v[150:153], v[194:197], v[20:23]
	v_mfma_f32_16x16x32_bf16 v[16:19], v[158:161], v[194:197], v[16:19]
	v_mfma_f32_16x16x32_bf16 v[60:63], v[154:157], v[174:177], v[60:63]
	v_mfma_f32_16x16x32_bf16 v[56:59], v[162:165], v[174:177], v[56:59]
	v_mfma_f32_16x16x32_bf16 v[52:55], v[154:157], v[182:185], v[52:55]
	v_mfma_f32_16x16x32_bf16 v[48:51], v[162:165], v[182:185], v[48:51]
	v_mfma_f32_16x16x32_bf16 v[36:39], v[154:157], v[190:193], v[36:39]
	v_mfma_f32_16x16x32_bf16 v[32:35], v[162:165], v[190:193], v[32:35]
	v_mfma_f32_16x16x32_bf16 v[20:23], v[154:157], v[198:201], v[20:23]
	v_mfma_f32_16x16x32_bf16 v[16:19], v[162:165], v[198:201], v[16:19]
	s_barrier
	s_add_u32 s0, s54, 0x80000
	s_addc_u32 s1, s55, 0
	s_add_i32 s84, s76, s58
	s_mov_b32 m0, s84
	v_lshl_add_u64 v[150:151], s[0:1], 0, v[132:133]
	global_load_lds_dwordx4 v[150:151], off
	s_add_i32 m0, s84, 0x2000
	v_lshl_add_u64 v[150:151], s[0:1], 0, v[128:129]
	global_load_lds_dwordx4 v[150:151], off
	s_waitcnt vmcnt(6)
	s_barrier
; #define PG8_STAGE(bufoff, gbase, voff) do { _Pragma("unroll") for (int _i = 0; _i < 2; ++_i) \
;         __builtin_amdgcn_global_load_lds((const unsigned*)((const char*)(gbase) + (voff)[_i]), (LAS unsigned*)(lds + (bufoff) + ldsw + _i * 8192), 16, 0, 0); } while (0)
; #define PG8_LDA(dst, b, h) do { _Pragma("unroll") for (int m = 0; m < 4; ++m) _Pragma("unroll") for (int k = 0; k < 2; ++k) dst[m][k] = *(const LAS bf16x8*)(lds + PG8_SA(b, h) + aoff + m * 2048 + k * 1024); } while (0)
; #define PG8_LDB(dst, b, h) do { _Pragma("unroll") for (int n = 0; n < 2; ++n) _Pragma("unroll") for (int k = 0; k < 2; ++k) dst[n][k] = *(const LAS bf16x8*)(lds + PG8_SB(b, h) + boff + n * 2048 + k * 1024); } while (0)
; #define PG8_MMA(ai, bj, At, Bt) do { __builtin_amdgcn_s_setprio(1); _Pragma("unroll") for (int m = 0; m < 4; ++m) _Pragma("unroll") for (int n = 0; n < 2; ++n) _Pragma("unroll") for (int k = 0; k < 2; ++k) \
;         acc[ai][bj][m][n] = __builtin_amdgcn_mfma_f32_16x16x32_bf16(Bt[n][k], At[m][k], acc[ai][bj][m][n], 0, 0, 0); __builtin_amdgcn_s_setprio(0); } while (0)
; #define PG8_WAIT_V(n) asm volatile("s_waitcnt vmcnt(" #n ")" ::: "memory")
; #define PG8_WAIT_L(n) asm volatile("s_waitcnt lgkmcnt(" #n ")" ::: "memory")
; #define PG8_BAR __builtin_amdgcn_s_barrier()
; #define PG8_SCHED __builtin_amdgcn_sched_barrier(0)
; template <class Epi>
; DI void gemm_phase(LAS unsigned char* lds, const Gemm g, const StaticOrder& S, const Epi& E) {
;     ...
;             PG8_STAGE(PG8_SB(0, 1), b2 + hstepB, voffB);
;             PG8_WAIT_V(6); PG8_BAR; PG8_MMA(1, 1, At, B1); PG8_BAR;
;             PG8_LDB(B0, 1, 0); PG8_SCHED; PG8_LDA(At, 1, 0); PG8_STAGE(PG8_SA(0, 1), a2 + hstepA, voffA);
;             PG8_WAIT_L(8); PG8_BAR; PG8_WAIT_L(0); PG8_MMA(0, 0, At, B0); PG8_BAR; PG8_SCHED;
;             PG8_LDB(B1, 1, 1); PG8_STAGE(PG8_SB(1, 0), b3, voffB);
;             PG8_BAR; PG8_WAIT_L(0); PG8_MMA(0, 1, At, B1); PG8_BAR;
;             PG8_LDA(At, 1, 1); PG8_STAGE(PG8_SA(1, 0), a3, voffA);
;             PG8_BAR; PG8_WAIT_L(0); PG8_MMA(1, 0, At, B0); PG8_BAR; PG8_SCHED;
	v_mfma_f32_16x16x32_bf16 v[44:47], v[202:205], v[166:169], v[44:47]
	v_mfma_f32_16x16x32_bf16 v[40:43], v[210:213], v[166:169], v[40:43]
	v_mfma_f32_16x16x32_bf16 v[28:31], v[202:205], v[178:181], v[28:31]
	v_mfma_f32_16x16x32_bf16 v[24:27], v[210:213], v[178:181], v[24:27]
	v_mfma_f32_16x16x32_bf16 v[12:15], v[202:205], v[186:189], v[12:15]
	v_mfma_f32_16x16x32_bf16 v[8:11], v[210:213], v[186:189], v[8:11]
	v_mfma_f32_16x16x32_bf16 v[4:7], v[202:205], v[194:197], v[4:7]
	v_mfma_f32_16x16x32_bf16 v[0:3], v[210:213], v[194:197], v[0:3]
	v_mfma_f32_16x16x32_bf16 v[44:47], v[206:209], v[174:177], v[44:47]
	v_mfma_f32_16x16x32_bf16 v[40:43], v[216:219], v[174:177], v[40:43]
	v_mfma_f32_16x16x32_bf16 v[28:31], v[206:209], v[182:185], v[28:31]
	v_mfma_f32_16x16x32_bf16 v[24:27], v[216:219], v[182:185], v[24:27]
	v_mfma_f32_16x16x32_bf16 v[12:15], v[206:209], v[190:193], v[12:15]
	v_mfma_f32_16x16x32_bf16 v[8:11], v[216:219], v[190:193], v[8:11]
	v_mfma_f32_16x16x32_bf16 v[4:7], v[206:209], v[198:201], v[4:7]
	v_mfma_f32_16x16x32_bf16 v[0:3], v[216:219], v[198:201], v[0:3]
	s_add_i32 s84, 0, 0x18000
	v_add_u32_e32 v162, s84, v145
	s_barrier
	ds_read_b128 v[150:153], v162
	ds_read_b128 v[154:157], v162 offset:1024
	ds_read_b128 v[158:161], v162 offset:2048
	ds_read_b128 v[162:165], v162 offset:3072
	s_add_u32 s0, s56, 0x80000
	s_addc_u32 s1, s57, 0
	s_mov_b32 m0, s68
	v_lshl_add_u64 v[202:203], s[0:1], 0, v[134:135]
	ds_read_b128 v[166:169], v148 offset:32768
	ds_read_b128 v[174:177], v148 offset:33792
	ds_read_b128 v[178:181], v148 offset:34816
	ds_read_b128 v[182:185], v148 offset:35840
	ds_read_b128 v[186:189], v148 offset:36864
	ds_read_b128 v[190:193], v148 offset:37888
	ds_read_b128 v[194:197], v148 offset:38912
	ds_read_b128 v[198:201], v148 offset:39936
	global_load_lds_dwordx4 v[202:203], off
	s_mov_b32 m0, s69
	v_lshl_add_u64 v[202:203], s[0:1], 0, v[130:131]
	global_load_lds_dwordx4 v[202:203], off
	s_waitcnt lgkmcnt(8)
	s_barrier
	s_waitcnt lgkmcnt(0)
	v_mfma_f32_16x16x32_bf16 v[124:127], v[150:153], v[166:169], v[124:127]
	v_mfma_f32_16x16x32_bf16 v[120:123], v[158:161], v[166:169], v[120:123]
	v_mfma_f32_16x16x32_bf16 v[116:119], v[150:153], v[178:181], v[116:119]
	v_mfma_f32_16x16x32_bf16 v[112:115], v[158:161], v[178:181], v[112:115]
	v_mfma_f32_16x16x32_bf16 v[100:103], v[150:153], v[186:189], v[100:103]
	v_mfma_f32_16x16x32_bf16 v[96:99], v[158:161], v[186:189], v[96:99]
	v_mfma_f32_16x16x32_bf16 v[84:87], v[150:153], v[194:197], v[84:87]
	v_mfma_f32_16x16x32_bf16 v[80:83], v[158:161], v[194:197], v[80:83]
	v_mfma_f32_16x16x32_bf16 v[124:127], v[154:157], v[174:177], v[124:127]
	v_mfma_f32_16x16x32_bf16 v[120:123], v[162:165], v[174:177], v[120:123]
	v_mfma_f32_16x16x32_bf16 v[116:119], v[154:157], v[182:185], v[116:119]
	v_mfma_f32_16x16x32_bf16 v[112:115], v[162:165], v[182:185], v[112:115]
	v_mfma_f32_16x16x32_bf16 v[100:103], v[154:157], v[190:193], v[100:103]
	v_mfma_f32_16x16x32_bf16 v[96:99], v[162:165], v[190:193], v[96:99]
	v_mfma_f32_16x16x32_bf16 v[84:87], v[154:157], v[198:201], v[84:87]
	v_mfma_f32_16x16x32_bf16 v[80:83], v[162:165], v[198:201], v[80:83]
	s_barrier
	s_add_i32 s56, 0, 0x1c000
	s_add_i32 s0, s84, s58
	v_add_u32_e32 v172, s56, v145
	v_lshl_add_u64 v[170:171], v[170:171], 0, s[4:5]
	s_mov_b32 m0, s0
	ds_read_b128 v[202:205], v172
	ds_read_b128 v[206:209], v172 offset:1024
	ds_read_b128 v[210:213], v172 offset:2048
	ds_read_b128 v[216:219], v172 offset:3072
	global_load_lds_dwordx4 v[170:171], off
	s_add_i32 m0, s0, 0x2000
	v_lshl_add_u64 v[170:171], v[220:221], 0, s[4:5]
	global_load_lds_dwordx4 v[170:171], off
	s_barrier
	s_waitcnt lgkmcnt(0)
	v_mfma_f32_16x16x32_bf16 v[108:111], v[202:205], v[166:169], v[108:111]
	v_mfma_f32_16x16x32_bf16 v[104:107], v[210:213], v[166:169], v[104:107]
	v_mfma_f32_16x16x32_bf16 v[92:95], v[202:205], v[178:181], v[92:95]
	v_mfma_f32_16x16x32_bf16 v[88:91], v[210:213], v[178:181], v[88:91]
	v_mfma_f32_16x16x32_bf16 v[76:79], v[202:205], v[186:189], v[76:79]
	v_mfma_f32_16x16x32_bf16 v[72:75], v[210:213], v[186:189], v[72:75]
	v_mfma_f32_16x16x32_bf16 v[68:71], v[202:205], v[194:197], v[68:71]
	v_mfma_f32_16x16x32_bf16 v[64:67], v[210:213], v[194:197], v[64:67]
	v_mfma_f32_16x16x32_bf16 v[108:111], v[206:209], v[174:177], v[108:111]
	v_mfma_f32_16x16x32_bf16 v[104:107], v[216:219], v[174:177], v[104:107]
	v_mfma_f32_16x16x32_bf16 v[92:95], v[206:209], v[182:185], v[92:95]
	v_mfma_f32_16x16x32_bf16 v[88:91], v[216:219], v[182:185], v[88:91]
	v_mfma_f32_16x16x32_bf16 v[76:79], v[206:209], v[190:193], v[76:79]
	v_mfma_f32_16x16x32_bf16 v[72:75], v[216:219], v[190:193], v[72:75]
	v_mfma_f32_16x16x32_bf16 v[68:71], v[206:209], v[198:201], v[68:71]
	v_mfma_f32_16x16x32_bf16 v[64:67], v[216:219], v[198:201], v[64:67]
	s_mov_b32 m0, s71
	v_lshl_add_u64 v[170:171], v[222:223], 0, s[4:5]
	s_barrier
	ds_read_b128 v[166:169], v148 offset:49152
	ds_read_b128 v[174:177], v148 offset:50176
	ds_read_b128 v[178:181], v148 offset:51200
	ds_read_b128 v[182:185], v148 offset:52224
	ds_read_b128 v[186:189], v148 offset:53248
	ds_read_b128 v[190:193], v148 offset:54272
	ds_read_b128 v[194:197], v148 offset:55296
	ds_read_b128 v[198:201], v148 offset:56320
	global_load_lds_dwordx4 v[170:171], off
	s_mov_b32 m0, s72
	v_lshl_add_u64 v[170:171], v[224:225], 0, s[4:5]
	global_load_lds_dwordx4 v[170:171], off
	s_barrier
; #define PG8_STAGE(bufoff, gbase, voff) do { _Pragma("unroll") for (int _i = 0; _i < 2; ++_i) \
;         __builtin_amdgcn_global_load_lds((const unsigned*)((const char*)(gbase) + (voff)[_i]), (LAS unsigned*)(lds + (bufoff) + ldsw + _i * 8192), 16, 0, 0); } while (0)
; #define PG8_LDA(dst, b, h) do { _Pragma("unroll") for (int m = 0; m < 4; ++m) _Pragma("unroll") for (int k = 0; k < 2; ++k) dst[m][k] = *(const LAS bf16x8*)(lds + PG8_SA(b, h) + aoff + m * 2048 + k * 1024); } while (0)
; #define PG8_MMA(ai, bj, At, Bt) do { __builtin_amdgcn_s_setprio(1); _Pragma("unroll") for (int m = 0; m < 4; ++m) _Pragma("unroll") for (int n = 0; n < 2; ++n) _Pragma("unroll") for (int k = 0; k < 2; ++k) \
;         acc[ai][bj][m][n] = __builtin_amdgcn_mfma_f32_16x16x32_bf16(Bt[n][k], At[m][k], acc[ai][bj][m][n], 0, 0, 0); __builtin_amdgcn_s_setprio(0); } while (0)
; #define PG8_WAIT_V(n) asm volatile("s_waitcnt vmcnt(" #n ")" ::: "memory")
; #define PG8_WAIT_L(n) asm volatile("s_waitcnt lgkmcnt(" #n ")" ::: "memory")
; #define PG8_BAR __builtin_amdgcn_s_barrier()
; #define PG8_SCHED __builtin_amdgcn_sched_barrier(0)
; template <class Epi>
; DI void gemm_phase(LAS unsigned char* lds, const Gemm g, const StaticOrder& S, const Epi& E) {
;     ...
;             PG8_BAR; PG8_WAIT_L(0); PG8_MMA(0, 1, At, B1); PG8_BAR;
;             PG8_LDA(At, 1, 1); PG8_STAGE(PG8_SA(1, 0), a3, voffA);
;             PG8_BAR; PG8_WAIT_L(0); PG8_MMA(1, 0, At, B0); PG8_BAR; PG8_SCHED;
;             PG8_STAGE(PG8_SB(1, 1), b3 + hstepB, voffB);
;             PG8_WAIT_V(6); PG8_BAR; PG8_MMA(1, 1, At, B1); PG8_BAR;
;         }
	s_waitcnt lgkmcnt(0)
	v_mfma_f32_16x16x32_bf16 v[60:63], v[150:153], v[166:169], v[60:63]
	v_mfma_f32_16x16x32_bf16 v[56:59], v[158:161], v[166:169], v[56:59]
	v_mfma_f32_16x16x32_bf16 v[52:55], v[150:153], v[178:181], v[52:55]
	v_mfma_f32_16x16x32_bf16 v[48:51], v[158:161], v[178:181], v[48:51]
	v_mfma_f32_16x16x32_bf16 v[36:39], v[150:153], v[186:189], v[36:39]
	v_mfma_f32_16x16x32_bf16 v[32:35], v[158:161], v[186:189], v[32:35]
	v_mfma_f32_16x16x32_bf16 v[20:23], v[150:153], v[194:197], v[20:23]
	v_mfma_f32_16x16x32_bf16 v[16:19], v[158:161], v[194:197], v[16:19]
	v_mfma_f32_16x16x32_bf16 v[60:63], v[154:157], v[174:177], v[60:63]
	v_mfma_f32_16x16x32_bf16 v[56:59], v[162:165], v[174:177], v[56:59]
	v_mfma_f32_16x16x32_bf16 v[52:55], v[154:157], v[182:185], v[52:55]
	v_mfma_f32_16x16x32_bf16 v[48:51], v[162:165], v[182:185], v[48:51]
	v_mfma_f32_16x16x32_bf16 v[36:39], v[154:157], v[190:193], v[36:39]
	v_mfma_f32_16x16x32_bf16 v[32:35], v[162:165], v[190:193], v[32:35]
	v_mfma_f32_16x16x32_bf16 v[20:23], v[154:157], v[198:201], v[20:23]
	v_mfma_f32_16x16x32_bf16 v[16:19], v[162:165], v[198:201], v[16:19]
	s_barrier
	s_add_u32 s0, s54, 0x80080
	s_addc_u32 s1, s55, 0
	s_add_i32 s54, s56, s58
	s_mov_b32 m0, s54
	v_lshl_add_u64 v[150:151], s[0:1], 0, v[132:133]
	global_load_lds_dwordx4 v[150:151], off
	s_add_i32 m0, s54, 0x2000
	v_lshl_add_u64 v[150:151], s[0:1], 0, v[128:129]
	global_load_lds_dwordx4 v[150:151], off
	s_waitcnt vmcnt(6)
	s_barrier
	v_mfma_f32_16x16x32_bf16 v[44:47], v[202:205], v[166:169], v[44:47]
	v_mfma_f32_16x16x32_bf16 v[40:43], v[210:213], v[166:169], v[40:43]
	v_mfma_f32_16x16x32_bf16 v[28:31], v[202:205], v[178:181], v[28:31]
	v_mfma_f32_16x16x32_bf16 v[24:27], v[210:213], v[178:181], v[24:27]
	v_mfma_f32_16x16x32_bf16 v[12:15], v[202:205], v[186:189], v[12:15]
	v_mfma_f32_16x16x32_bf16 v[8:11], v[210:213], v[186:189], v[8:11]
	v_mfma_f32_16x16x32_bf16 v[4:7], v[202:205], v[194:197], v[4:7]
	v_mfma_f32_16x16x32_bf16 v[0:3], v[210:213], v[194:197], v[0:3]
	v_mfma_f32_16x16x32_bf16 v[44:47], v[206:209], v[174:177], v[44:47]
	v_mfma_f32_16x16x32_bf16 v[40:43], v[216:219], v[174:177], v[40:43]
	v_mfma_f32_16x16x32_bf16 v[28:31], v[206:209], v[182:185], v[28:31]
	v_mfma_f32_16x16x32_bf16 v[24:27], v[216:219], v[182:185], v[24:27]
	v_mfma_f32_16x16x32_bf16 v[12:15], v[206:209], v[190:193], v[12:15]
	v_mfma_f32_16x16x32_bf16 v[8:11], v[216:219], v[190:193], v[8:11]
	v_mfma_f32_16x16x32_bf16 v[4:7], v[206:209], v[198:201], v[4:7]
	v_mfma_f32_16x16x32_bf16 v[0:3], v[216:219], v[198:201], v[0:3]
	s_add_i32 s83, s83, 2
	s_add_u32 s52, s52, 0x100
	s_addc_u32 s53, s53, 0
	s_add_u32 s81, s81, 0x100
	s_addc_u32 s82, s82, 0
	s_cmp_gt_u32 s83, 29
	s_barrier
	s_cbranch_scc0 .LBB0_113
; DI unsigned pk2(float lo, float hi) { f32x2 v = {lo, hi}; bf16x2_t b = __builtin_convertvector(v, bf16x2_t); return __builtin_bit_cast(unsigned, b); }
; #define PG8_WAIT_V(n) asm volatile("s_waitcnt vmcnt(" #n ")" ::: "memory")
; #define PG8_BAR __builtin_amdgcn_s_barrier()
; template <class Epi>
; DI void gemm_phase(LAS unsigned char* lds, const Gemm g, const StaticOrder& S, const Epi& E) {
;     ...
;         E(acc, cur, wr, wc, fr, fq);
;         if (!has_next) break;
; #pragma unroll
;         for (int a = 0; a < 2; ++a)
; #pragma unroll
;             for (int b = 0; b < 2; ++b)
; #pragma unroll
;                 for (int m = 0; m < 4; ++m)
; #pragma unroll
;                     for (int n = 0; n < 2; ++n) acc[a][b][m][n] = (f32x4){0.f, 0.f, 0.f, 0.f};
;         cur = nxt; cA = nA; cB = nB; ++ui;
;     }
;     PG8_WAIT_V(0);
;     if (wr == 0) PG8_BAR;
;     PG8_BAR;
;     DI void operator()(const f32x4 (&acc)[2][2][4][2], const Unit& u, int wr, int wc, int fr, int fq) const {
;         const int row0 = u.pm * BM + wr * 64 + fr, col0 = u.pn * BM + wc * 32 + 8 * fq;
; #pragma unroll
;         for (int ai = 0; ai < 2; ++ai)
; #pragma unroll
;             for (int m = 0; m < 4; ++m) { bf16_t* rowp = O + (size_t)(row0 + ai * HALF + m * 16) * ldc + col0;
; #pragma unroll
;                 for (int bj = 0; bj < 2; ++bj) { const f32x4 v0 = acc[ai][bj][m][0], v1 = acc[ai][bj][m][1];
;                     u32x4 w; w.x = pk2(v0[0], v0[1]); w.y = pk2(v0[2], v0[3]); w.z = pk2(v1[0], v1[1]); w.w = pk2(v1[2], v1[3]);
;                     *(u32x4*)(rowp + bj * HALF) = w; } }
	v_lshl_add_u32 v156, s8, 8, v144
	v_lshl_or_b32 v150, s78, 8, v146
	v_ashrrev_i32_e32 v151, 31, v150
	v_mov_b64_e32 v[152:153], s[30:31]
	v_cvt_pk_bf16_f32 v68, v68, v69
	v_cvt_pk_bf16_f32 v69, v70, v71
	v_cvt_pk_bf16_f32 v70, v64, v65
	v_add_u32_e32 v64, 0x80, v156
	v_mad_i64_i32 v[154:155], s[0:1], v156, s77, v[152:153]
	v_lshlrev_b64 v[150:151], 1, v[150:151]
	v_cvt_pk_bf16_f32 v108, v108, v109
	v_cvt_pk_bf16_f32 v109, v110, v111
	v_cvt_pk_bf16_f32 v110, v104, v105
	v_or_b32_e32 v104, 16, v156
	v_mad_i64_i32 v[64:65], s[0:1], v64, s77, v[152:153]
	v_cvt_pk_bf16_f32 v44, v44, v45
	v_cvt_pk_bf16_f32 v45, v46, v47
	v_cvt_pk_bf16_f32 v46, v40, v41
	v_add_u32_e32 v40, 0x90, v156
	v_lshl_add_u64 v[154:155], v[154:155], 0, v[150:151]
	v_cvt_pk_bf16_f32 v111, v106, v107
	v_mad_i64_i32 v[104:105], s[0:1], v104, s77, v[152:153]
	v_cvt_pk_bf16_f32 v92, v92, v93
	v_cvt_pk_bf16_f32 v93, v94, v95
	v_cvt_pk_bf16_f32 v94, v88, v89
	v_or_b32_e32 v88, 32, v156
	v_lshl_add_u64 v[64:65], v[64:65], 0, v[150:151]
	v_cvt_pk_bf16_f32 v47, v42, v43
	v_mad_i64_i32 v[40:41], s[0:1], v40, s77, v[152:153]
	v_cvt_pk_bf16_f32 v28, v28, v29
	v_cvt_pk_bf16_f32 v29, v30, v31
	v_cvt_pk_bf16_f32 v30, v24, v25
	v_add_u32_e32 v24, 0xa0, v156
	global_store_dwordx4 v[154:155], v[108:111], off offset:256 nt
	v_cvt_pk_bf16_f32 v95, v90, v91
	v_mad_i64_i32 v[88:89], s[0:1], v88, s77, v[152:153]
	v_lshl_add_u64 v[108:109], v[104:105], 0, v[150:151]
	v_cvt_pk_bf16_f32 v76, v76, v77
	v_cvt_pk_bf16_f32 v77, v78, v79
	v_cvt_pk_bf16_f32 v78, v72, v73
	v_or_b32_e32 v72, 48, v156
	global_store_dwordx4 v[64:65], v[44:47], off offset:256 nt
	v_cvt_pk_bf16_f32 v31, v26, v27
	v_mad_i64_i32 v[24:25], s[0:1], v24, s77, v[152:153]
	v_lshl_add_u64 v[44:45], v[40:41], 0, v[150:151]
	v_cvt_pk_bf16_f32 v12, v12, v13
	v_cvt_pk_bf16_f32 v13, v14, v15
	v_cvt_pk_bf16_f32 v14, v8, v9
	v_add_u32_e32 v8, 0xb0, v156
	global_store_dwordx4 v[108:109], v[92:95], off offset:256 nt
	v_cvt_pk_bf16_f32 v79, v74, v75
	v_mad_i64_i32 v[72:73], s[0:1], v72, s77, v[152:153]
	v_lshl_add_u64 v[92:93], v[88:89], 0, v[150:151]
	global_store_dwordx4 v[44:45], v[28:31], off offset:256 nt
	v_cvt_pk_bf16_f32 v15, v10, v11
	v_mad_i64_i32 v[8:9], s[0:1], v8, s77, v[152:153]
	v_lshl_add_u64 v[28:29], v[24:25], 0, v[150:151]
	v_cvt_pk_bf16_f32 v124, v124, v125
	v_cvt_pk_bf16_f32 v125, v126, v127
	v_cvt_pk_bf16_f32 v126, v120, v121
	v_cvt_pk_bf16_f32 v127, v122, v123
	v_cvt_pk_bf16_f32 v104, v116, v117
	v_cvt_pk_bf16_f32 v105, v118, v119
	v_cvt_pk_bf16_f32 v106, v112, v113
	v_cvt_pk_bf16_f32 v107, v114, v115
	v_cvt_pk_bf16_f32 v88, v100, v101
	v_cvt_pk_bf16_f32 v89, v102, v103
	v_cvt_pk_bf16_f32 v90, v96, v97
	v_cvt_pk_bf16_f32 v91, v98, v99
	global_store_dwordx4 v[92:93], v[76:79], off offset:256 nt
	v_cvt_pk_bf16_f32 v74, v80, v81
	v_cvt_pk_bf16_f32 v75, v82, v83
	v_lshl_add_u64 v[76:77], v[72:73], 0, v[150:151]
	v_cvt_pk_bf16_f32 v72, v84, v85
	v_cvt_pk_bf16_f32 v73, v86, v87
	v_cvt_pk_bf16_f32 v71, v66, v67
	v_cvt_pk_bf16_f32 v60, v60, v61
	v_cvt_pk_bf16_f32 v61, v62, v63
	v_cvt_pk_bf16_f32 v62, v56, v57
	v_cvt_pk_bf16_f32 v63, v58, v59
	v_cvt_pk_bf16_f32 v40, v52, v53
	v_cvt_pk_bf16_f32 v41, v54, v55
	v_cvt_pk_bf16_f32 v42, v48, v49
	v_cvt_pk_bf16_f32 v43, v50, v51
	v_cvt_pk_bf16_f32 v24, v36, v37
	v_cvt_pk_bf16_f32 v25, v38, v39
	v_cvt_pk_bf16_f32 v26, v32, v33
	v_cvt_pk_bf16_f32 v27, v34, v35
	global_store_dwordx4 v[28:29], v[12:15], off offset:256 nt
	v_cvt_pk_bf16_f32 v10, v16, v17
	v_cvt_pk_bf16_f32 v11, v18, v19
	v_lshl_add_u64 v[12:13], v[8:9], 0, v[150:151]
	v_cvt_pk_bf16_f32 v8, v20, v21
	v_cvt_pk_bf16_f32 v9, v22, v23
	v_cvt_pk_bf16_f32 v4, v4, v5
	v_cvt_pk_bf16_f32 v5, v6, v7
	v_cvt_pk_bf16_f32 v6, v0, v1
	v_cvt_pk_bf16_f32 v7, v2, v3
	s_and_b64 vcc, exec, s[2:3]
	s_mov_b32 s78, s16
	s_mov_b32 s8, s46
	s_mov_b64 s[54:55], s[50:51]
	s_mov_b64 s[52:53], s[48:49]
	global_store_dwordx4 v[154:155], v[124:127], off nt
	global_store_dwordx4 v[108:109], v[104:107], off nt
	global_store_dwordx4 v[92:93], v[88:91], off nt
	global_store_dwordx4 v[76:77], v[72:75], off nt
	global_store_dwordx4 v[76:77], v[68:71], off offset:256 nt
	global_store_dwordx4 v[64:65], v[60:63], off nt
	global_store_dwordx4 v[44:45], v[40:43], off nt
	global_store_dwordx4 v[28:29], v[24:27], off nt
	global_store_dwordx4 v[12:13], v[8:11], off nt
	global_store_dwordx4 v[12:13], v[4:7], off offset:256 nt
	s_cbranch_vccz .LBB0_110
	s_waitcnt vmcnt(0)
	s_cmpk_gt_u32 s33, 0xff
	s_cbranch_scc1 .LBB0_117
	s_barrier
